# mixer A step loop: x-row load waits no longer drain the 32 stores (vmcnt 33/32), conv block LDS reads batched, gate-loop LDS operands read one half-iteration ahead
# speedup vs baseline: 1.0024x; 1.0024x over previous
.LBB0_1111:
	s_waitcnt vmcnt(0)
	v_mul_f32_e32 v2, 0xbfb8aa3b, v68
	v_exp_f32_e32 v83, v2
	s_mov_b32 s18, 0x3f2aaaab
	s_lshl_b32 s24, s7, 1
	v_mov_b32_e32 v81, v3
	v_add_f32_e32 v70, 1.0, v83
	v_add_f32_e32 v68, -1.0, v70
	v_sub_f32_e32 v69, v68, v70
	v_sub_f32_e32 v68, v83, v68
	v_add_f32_e32 v69, 1.0, v69
	v_frexp_mant_f32_e32 v71, v70
	v_add_f32_e32 v72, v68, v69
	v_cvt_f64_f32_e32 v[68:69], v70
	v_frexp_exp_i32_f64_e32 v68, v[68:69]
	v_cmp_gt_f32_e32 vcc, s18, v71
	s_mov_b32 s7, 0x3f317218
	v_mov_b32_e32 v2, 1.0
	v_subbrev_co_u32_e32 v85, vcc, 0, v68, vcc
	v_sub_u32_e32 v68, 0, v85
	v_ldexp_f32 v69, v70, v68
	v_add_f32_e32 v70, -1.0, v69
	v_add_f32_e32 v73, 1.0, v69
	v_add_f32_e32 v71, 1.0, v70
	v_add_f32_e32 v74, -1.0, v73
	v_ldexp_f32 v68, v72, v68
	v_sub_f32_e32 v71, v69, v71
	v_sub_f32_e32 v69, v69, v74
	v_add_f32_e32 v71, v68, v71
	v_add_f32_e32 v68, v68, v69
	v_add_f32_e32 v69, v73, v68
	v_rcp_f32_e32 v87, v69
	v_add_f32_e32 v72, v70, v71
	v_sub_f32_e32 v70, v72, v70
	v_sub_f32_e32 v70, v71, v70
	v_sub_f32_e32 v71, v69, v73
	v_mul_f32_e32 v88, v72, v87
	v_sub_f32_e32 v68, v68, v71
	v_mul_f32_e32 v71, v69, v88
	v_fma_f32 v73, v88, v69, -v71
	v_fmac_f32_e32 v73, v88, v68
	v_add_f32_e32 v74, v71, v73
	v_sub_f32_e32 v75, v72, v74
	v_sub_f32_e32 v72, v72, v75
	v_sub_f32_e32 v71, v74, v71
	v_sub_f32_e32 v72, v72, v74
	v_add_f32_e32 v70, v70, v72
	v_sub_f32_e32 v71, v71, v73
	v_add_f32_e32 v70, v71, v70
	v_add_f32_e32 v71, v75, v70
	v_mul_f32_e32 v89, v87, v71
	v_mul_f32_e32 v72, v69, v89
	v_fma_f32 v69, v89, v69, -v72
	v_fmac_f32_e32 v69, v89, v68
	v_sub_f32_e32 v68, v75, v71
	v_add_f32_e32 v68, v70, v68
	v_add_f32_e32 v70, v72, v69
	v_sub_f32_e32 v90, v71, v70
	v_sub_f32_e32 v71, v71, v90
	v_sub_f32_e32 v72, v70, v72
	v_sub_f32_e32 v70, v71, v70
	v_add_f32_e32 v91, v68, v70
	v_sub_f32_e32 v92, v72, v69
	v_add_u32_e32 v70, s6, v117
	v_mov_b64_e32 v[68:69], s[16:17]
	v_mad_i64_i32 v[68:69], s[18:19], v70, s69, v[68:69]
	v_lshl_add_u64 v[68:69], v[68:69], 0, s[24:25]
	v_lshl_add_u64 v[98:99], v[68:69], 0, v[80:81]
	v_add_co_u32_e32 v72, vcc, 0x9000, v98
	v_add_f32_e32 v81, v92, v91
	s_nop 0
	v_addc_co_u32_e32 v73, vcc, 0, v99, vcc
	global_load_dwordx4 v[68:71], v[98:99], off
	s_nop 0
	global_load_dwordx4 v[72:75], v[72:73], off
	v_add_f32_e32 v81, v90, v81
	v_cvt_f32_i32_e32 v85, v85
	v_mul_f32_e32 v81, v87, v81
	v_add_f32_e32 v87, v88, v89
	v_sub_f32_e32 v88, v87, v88
	v_sub_f32_e32 v88, v89, v88
	v_add_f32_e32 v81, v88, v81
	v_mul_f32_e32 v91, 0x3f317218, v85
	v_add_f32_e32 v88, v87, v81
	v_fma_f32 v92, v85, s7, -v91
	v_mul_f32_e32 v89, v88, v88
	v_mov_b32_e32 v90, 0x3ecc95a3
	v_fmac_f32_e32 v92, 0xb102e308, v85
	v_sub_f32_e32 v85, v88, v87
	v_fmamk_f32 v90, v89, 0x3e9b6dac, v90
	v_sub_f32_e32 v81, v81, v85
	v_add_f32_e32 v85, v91, v92
	v_fmaak_f32 v90, v89, v90, 0x3f2aaada
	v_sub_f32_e32 v87, v85, v91
	v_ldexp_f32 v91, v88, 1
	v_mul_f32_e32 v88, v88, v89
	v_mul_f32_e32 v88, v88, v90
	v_add_f32_e32 v89, v91, v88
	v_sub_f32_e32 v90, v89, v91
	v_ldexp_f32 v81, v81, 1
	v_sub_f32_e32 v88, v88, v90
	v_add_f32_e32 v81, v81, v88
	v_add_f32_e32 v88, v89, v81
	v_sub_f32_e32 v89, v88, v89
	v_sub_f32_e32 v81, v81, v89
	v_add_f32_e32 v89, v85, v88
	v_sub_f32_e32 v90, v89, v85
	v_sub_f32_e32 v91, v89, v90
	v_sub_f32_e32 v87, v92, v87
	v_sub_f32_e32 v85, v85, v91
	v_sub_f32_e32 v88, v88, v90
	v_add_f32_e32 v85, v88, v85
	v_add_f32_e32 v88, v87, v81
	v_sub_f32_e32 v90, v88, v87
	v_sub_f32_e32 v91, v88, v90
	v_sub_f32_e32 v87, v87, v91
	v_sub_f32_e32 v81, v81, v90
	v_add_f32_e32 v85, v88, v85
	v_add_f32_e32 v81, v81, v87
	v_add_f32_e32 v87, v89, v85
	v_sub_f32_e32 v88, v87, v89
	v_sub_f32_e32 v85, v85, v88
	v_add_f32_e32 v81, v81, v85
	s_mov_b32 s18, 0x7f800000
	v_add_f32_e32 v81, v87, v81
	v_cmp_neq_f32_e32 vcc, s18, v83
	v_mov_b32_e32 v85, 0x7f800000
	s_mov_b32 s7, 0x33800000
	v_cndmask_b32_e32 v81, v85, v81, vcc
	v_cmp_ngt_f32_e32 vcc, -1.0, v83
	v_mov_b32_e32 v85, 0x7fc00000
	s_mov_b32 s28, 0
	v_cndmask_b32_e32 v81, v85, v81, vcc
	v_cmp_neq_f32_e32 vcc, -1.0, v83
	v_mov_b32_e32 v85, v84
	v_mov_b32_e32 v87, v86
	v_cndmask_b32_e32 v81, v239, v81, vcc
	v_cmp_lt_f32_e64 vcc, |v83|, s7
	s_ashr_i32 s7, s6, 31
	s_lshl_b64 s[6:7], s[6:7], 10
	s_add_u32 s18, s35, s6
	s_addc_u32 s19, s38, s7
	s_add_u32 s18, s18, s24
	s_addc_u32 s19, s19, 0
	s_add_u32 s6, s39, s6
	s_addc_u32 s7, s40, s7
	v_cndmask_b32_e32 v81, v81, v83, vcc
	s_add_u32 s6, s6, s24
	v_mov_b32_e32 v83, v3
	s_addc_u32 s7, s7, 0
	v_mul_f32_e32 v92, 0xc1000000, v81
	v_lshl_add_u64 v[88:89], s[18:19], 0, v[82:83]
	v_lshl_add_u64 v[90:91], s[6:7], 0, v[82:83]
	v_mov_b32_e32 v93, v92
	v_mov_b32_e32 v97, 0
	s_waitcnt vmcnt(0)
.LBB0_1112:
	s_add_i32 s28, s28, 1
	s_cmp_ge_u32 s28, s1
	v_lshl_add_u64 v[94:95], v[98:99], 0, s[48:49]
	s_waitcnt vmcnt(33)
	ds_write_b128 v118, v[68:71] offset:2560
	s_waitcnt vmcnt(32)
	ds_write_b128 v118, v[72:75] offset:3584
	s_cbranch_scc1 .LBB0_1114
	v_add_co_u32_e32 v72, vcc, 0x1b000, v98
	s_nop 1
	v_addc_co_u32_e32 v73, vcc, 0, v99, vcc
	global_load_dwordx4 v[68:71], v[94:95], off
	s_nop 0
	global_load_dwordx4 v[72:75], v[72:73], off
.LBB0_1114:
	s_waitcnt lgkmcnt(0)
	ds_read_u16 v148, v120 offset:2560
	ds_read_u16 v149, v120 offset:2688
	ds_read_u16 v150, v120 offset:2816
	ds_read_u16 v151, v120 offset:2944
	ds_read_u16 v152, v120 offset:3072
	ds_read_u16 v153, v120 offset:3200
	ds_read_u16 v154, v120 offset:3328
	ds_read_u16 v155, v120 offset:3456
	s_mov_b64 s[18:19], 0
	s_mov_b32 s24, -2
	v_add_u32_e32 v81, v120, v119
	s_waitcnt lgkmcnt(4)
	v_lshlrev_b32_e32 v148, 16, v148
	v_lshlrev_b32_e32 v149, 16, v149
	v_lshlrev_b32_e32 v150, 16, v150
	v_lshlrev_b32_e32 v151, 16, v151
	ds_read_u16 v156, v120 offset:3584
	ds_read_u16 v157, v120 offset:3712
	ds_read_u16 v158, v120 offset:3840
	ds_read_u16 v159, v120 offset:3968
	s_waitcnt lgkmcnt(4)
	v_lshlrev_b32_e32 v152, 16, v152
	v_lshlrev_b32_e32 v153, 16, v153
	v_lshlrev_b32_e32 v154, 16, v154
	v_lshlrev_b32_e32 v155, 16, v155
	ds_read_u16 v160, v120 offset:4096
	ds_read_u16 v161, v120 offset:4224
	ds_read_u16 v162, v120 offset:4352
	ds_read_u16 v163, v120 offset:4480
	v_mul_f32_e32 v164, v124, v130
	v_mul_f32_e32 v165, v124, v129
	v_mul_f32_e32 v166, v124, v131
	v_mul_f32_e32 v167, v124, v148
	v_fmac_f32_e32 v164, v125, v129
	v_fmac_f32_e32 v165, v125, v131
	v_fmac_f32_e32 v166, v125, v148
	v_fmac_f32_e32 v167, v125, v149
	v_fmac_f32_e32 v164, v126, v131
	v_fmac_f32_e32 v165, v126, v148
	v_fmac_f32_e32 v166, v126, v149
	v_fmac_f32_e32 v167, v126, v150
	v_fmac_f32_e32 v164, v127, v148
	v_fmac_f32_e32 v165, v127, v149
	v_fmac_f32_e32 v166, v127, v150
	v_fmac_f32_e32 v167, v127, v151
	v_add_f32_e32 v164, v128, v164
	v_add_f32_e32 v165, v128, v165
	v_add_f32_e32 v166, v128, v166
	v_add_f32_e32 v167, v128, v167
	v_cvt_pk_bf16_f32 v192, v164, v164
	v_cvt_pk_bf16_f32 v193, v165, v165
	v_cvt_pk_bf16_f32 v194, v166, v166
	v_cvt_pk_bf16_f32 v195, v167, v167
	v_mul_f32_e32 v168, v124, v149
	v_mul_f32_e32 v169, v124, v150
	v_mul_f32_e32 v170, v124, v151
	v_mul_f32_e32 v171, v124, v152
	v_fmac_f32_e32 v168, v125, v150
	v_fmac_f32_e32 v169, v125, v151
	v_fmac_f32_e32 v170, v125, v152
	v_fmac_f32_e32 v171, v125, v153
	v_fmac_f32_e32 v168, v126, v151
	v_fmac_f32_e32 v169, v126, v152
	v_fmac_f32_e32 v170, v126, v153
	v_fmac_f32_e32 v171, v126, v154
	v_fmac_f32_e32 v168, v127, v152
	v_fmac_f32_e32 v169, v127, v153
	v_fmac_f32_e32 v170, v127, v154
	v_fmac_f32_e32 v171, v127, v155
	v_add_f32_e32 v168, v128, v168
	v_add_f32_e32 v169, v128, v169
	v_add_f32_e32 v170, v128, v170
	v_add_f32_e32 v171, v128, v171
	v_cvt_pk_bf16_f32 v196, v168, v168
	v_cvt_pk_bf16_f32 v197, v169, v169
	v_cvt_pk_bf16_f32 v198, v170, v170
	v_cvt_pk_bf16_f32 v199, v171, v171
	s_waitcnt lgkmcnt(4)
	v_lshlrev_b32_e32 v156, 16, v156
	v_lshlrev_b32_e32 v157, 16, v157
	v_lshlrev_b32_e32 v158, 16, v158
	v_lshlrev_b32_e32 v159, 16, v159
	v_mul_f32_e32 v172, v124, v153
	v_mul_f32_e32 v173, v124, v154
	v_mul_f32_e32 v174, v124, v155
	v_mul_f32_e32 v175, v124, v156
	v_fmac_f32_e32 v172, v125, v154
	v_fmac_f32_e32 v173, v125, v155
	v_fmac_f32_e32 v174, v125, v156
	v_fmac_f32_e32 v175, v125, v157
	v_fmac_f32_e32 v172, v126, v155
	v_fmac_f32_e32 v173, v126, v156
	v_fmac_f32_e32 v174, v126, v157
	v_fmac_f32_e32 v175, v126, v158
	v_fmac_f32_e32 v172, v127, v156
	v_fmac_f32_e32 v173, v127, v157
	v_fmac_f32_e32 v174, v127, v158
	v_fmac_f32_e32 v175, v127, v159
	v_add_f32_e32 v172, v128, v172
	v_add_f32_e32 v173, v128, v173
	v_add_f32_e32 v174, v128, v174
	v_add_f32_e32 v175, v128, v175
	v_cvt_pk_bf16_f32 v200, v172, v172
	v_cvt_pk_bf16_f32 v201, v173, v173
	v_cvt_pk_bf16_f32 v202, v174, v174
	v_cvt_pk_bf16_f32 v203, v175, v175
	s_waitcnt lgkmcnt(0)
	v_lshlrev_b32_e32 v160, 16, v160
	v_lshlrev_b32_e32 v130, 16, v161
	v_lshlrev_b32_e32 v129, 16, v162
	v_lshlrev_b32_e32 v131, 16, v163
	v_mul_f32_e32 v176, v124, v157
	v_mul_f32_e32 v177, v124, v158
	v_mul_f32_e32 v178, v124, v159
	v_mul_f32_e32 v179, v124, v160
	v_fmac_f32_e32 v176, v125, v158
	v_fmac_f32_e32 v177, v125, v159
	v_fmac_f32_e32 v178, v125, v160
	v_fmac_f32_e32 v179, v125, v130
	v_fmac_f32_e32 v176, v126, v159
	v_fmac_f32_e32 v177, v126, v160
	v_fmac_f32_e32 v178, v126, v130
	v_fmac_f32_e32 v179, v126, v129
	v_fmac_f32_e32 v176, v127, v160
	v_fmac_f32_e32 v177, v127, v130
	v_fmac_f32_e32 v178, v127, v129
	v_fmac_f32_e32 v179, v127, v131
	v_add_f32_e32 v176, v128, v176
	v_add_f32_e32 v177, v128, v177
	v_add_f32_e32 v178, v128, v178
	v_add_f32_e32 v179, v128, v179
	v_cvt_pk_bf16_f32 v204, v176, v176
	v_cvt_pk_bf16_f32 v205, v177, v177
	v_cvt_pk_bf16_f32 v206, v178, v178
	v_cvt_pk_bf16_f32 v207, v179, v179
	ds_write_b16 v120, v192
	ds_write_b16 v120, v193 offset:144
	ds_write2st64_b32 v81, v164, v165 offset0:42 offset1:43
	ds_write_b16 v120, v194 offset:288
	ds_write_b16 v120, v195 offset:432
	ds_write2st64_b32 v81, v166, v167 offset0:44 offset1:45
	ds_write_b16 v120, v196 offset:576
	ds_write_b16 v120, v197 offset:720
	ds_write2st64_b32 v81, v168, v169 offset0:46 offset1:47
	ds_write_b16 v120, v198 offset:864
	ds_write_b16 v120, v199 offset:1008
	ds_write2st64_b32 v81, v170, v171 offset0:48 offset1:49
	ds_write_b16 v120, v200 offset:1152
	ds_write_b16 v120, v201 offset:1296
	ds_write2st64_b32 v81, v172, v173 offset0:50 offset1:51
	ds_write_b16 v120, v202 offset:1440
	ds_write_b16 v120, v203 offset:1584
	ds_write2st64_b32 v81, v174, v175 offset0:52 offset1:53
	ds_write_b16 v120, v204 offset:1728
	ds_write_b16 v120, v205 offset:1872
	ds_write2st64_b32 v81, v176, v177 offset0:54 offset1:55
	ds_write_b16 v120, v206 offset:2016
	ds_write_b16 v120, v207 offset:2160
	ds_write2st64_b32 v81, v178, v179 offset0:56 offset1:57
	s_waitcnt lgkmcnt(0)
	ds_read_b128 v[98:101], v121
	ds_read_b128 v[102:105], v121 offset:64
	s_waitcnt lgkmcnt(1)
	v_mfma_f32_16x16x32_bf16 v[106:109], v[98:101], v[4:7], 0
	v_add_u32_e32 v81, 0x800, v122
	v_add_u32_e32 v83, 0x1800, v122
	v_add_u32_e32 v96, 0xc00, v122
	v_mfma_f32_16x16x32_bf16 v[110:113], v[98:101], v[12:15], 0
	v_mfma_f32_16x16x32_bf16 v[132:135], v[98:101], v[20:23], 0
	v_mfma_f32_16x16x32_bf16 v[136:139], v[98:101], v[28:31], 0
	s_waitcnt lgkmcnt(0)
	v_mfma_f32_16x16x32_bf16 v[106:109], v[102:105], v[8:11], v[106:109]
	v_mfma_f32_16x16x32_bf16 v[110:113], v[102:105], v[16:19], v[110:113]
	v_mfma_f32_16x16x32_bf16 v[132:135], v[102:105], v[24:27], v[132:135]
	v_mfma_f32_16x16x32_bf16 v[136:139], v[102:105], v[32:35], v[136:139]
	s_nop 6
	ds_write2_b32 v81, v106, v132 offset0:128 offset1:144
	ds_write2_b32 v83, v110, v136 offset0:128 offset1:144
	ds_write2_b32 v81, v107, v133 offset0:192 offset1:208
	ds_write2_b32 v83, v111, v137 offset0:192 offset1:208
	v_add_u32_e32 v136, 0x1c00, v122
	ds_write2_b32 v96, v108, v134 offset1:16
	ds_write2_b32 v136, v112, v138 offset1:16
	ds_write2_b32 v96, v109, v135 offset0:64 offset1:80
	ds_write2_b32 v136, v113, v139 offset0:64 offset1:80
	v_mfma_f32_16x16x32_bf16 v[106:109], v[98:101], v[36:39], 0
	v_mfma_f32_16x16x32_bf16 v[132:135], v[98:101], v[52:55], 0
	v_mfma_f32_16x16x32_bf16 v[110:113], v[98:101], v[40:43], 0
	v_mfma_f32_16x16x32_bf16 v[98:101], v[98:101], v[56:59], 0
	v_mfma_f32_16x16x32_bf16 v[106:109], v[102:105], v[44:47], v[106:109]
	v_mfma_f32_16x16x32_bf16 v[132:135], v[102:105], v[60:63], v[132:135]
	v_mfma_f32_16x16x32_bf16 v[110:113], v[102:105], v[48:51], v[110:113]
	v_mfma_f32_16x16x32_bf16 v[98:101], v[102:105], v[64:67], v[98:101]
	s_nop 5
	ds_write2_b32 v81, v106, v132 offset0:160 offset1:176
	s_nop 0
	ds_write2_b32 v83, v110, v98 offset0:160 offset1:176
	ds_write2_b32 v81, v107, v133 offset0:224 offset1:240
	ds_write2_b32 v83, v111, v99 offset0:224 offset1:240
	ds_write2_b32 v96, v108, v134 offset0:32 offset1:48
	ds_write2_b32 v136, v112, v100 offset0:32 offset1:48
	ds_write2_b32 v96, v109, v135 offset0:96 offset1:112
	ds_write2_b32 v136, v113, v101 offset0:96 offset1:112
	s_waitcnt lgkmcnt(0)
	v_mov_b32_e32 v81, v123
	ds_read2st64_b32 v[208:209], v81 offset1:1
	ds_read2st64_b32 v[210:211], v81 offset0:16 offset1:17
	ds_read2st64_b32 v[212:213], v81 offset0:32 offset1:33
	s_branch .LBB0_1116

.LBB0_1116:
	ds_read2st64_b32 v[214:215], v81 offset0:2 offset1:3
	ds_read2st64_b32 v[216:217], v81 offset0:18 offset1:19
	ds_read2st64_b32 v[218:219], v81 offset0:34 offset1:35
	s_waitcnt lgkmcnt(5)
	v_pk_add_f32 v[100:101], v[84:85], v[208:209]
	s_nop 0
	v_pk_mul_f32 v[100:101], v[100:101], s[56:57] op_sel_hi:[1,0]
	s_nop 0
	v_exp_f32_e32 v100, v100
	v_exp_f32_e32 v101, v101
	s_nop 0
	v_pk_add_f32 v[100:101], v[100:101], 1.0 op_sel_hi:[1,0]
	s_nop 0
	v_rcp_f32_e32 v100, v100
	v_rcp_f32_e32 v101, v101
	s_nop 0
	v_pk_mul_f32 v[108:109], v[92:93], v[100:101]
	s_nop 0
	v_cmp_nlt_f32_e32 vcc, s97, v108
	v_cmp_nlt_f32_e64 s[6:7], s97, v109
	s_or_b64 s[6:7], vcc, s[6:7]
	v_pk_add_f32 v[100:101], v[108:109], v[108:109]
	s_and_saveexec_b64 s[26:27], s[6:7]
	s_xor_b64 s[26:27], exec, s[26:27]
	s_cbranch_execz .LBB0_1118
	v_mul_f32_e32 v83, 0x3fb8aa3b, v108
	v_exp_f32_e32 v104, v83
	v_mul_f32_e32 v83, 0x3fb8aa3b, v100
	v_mul_f32_e32 v96, 0x3fb8aa3b, v101
	v_rndne_f32_e32 v106, v83
	v_rndne_f32_e32 v107, v96
	v_mul_f32_e32 v105, 0x3fb8aa3b, v109
	v_pk_fma_f32 v[108:109], v[106:107], s[88:89], v[100:101] op_sel_hi:[1,0,1]
	v_cvt_i32_f32_e32 v83, v106
	v_pk_fma_f32 v[108:109], v[106:107], s[90:91], v[108:109] op_sel_hi:[1,0,1]
	v_cvt_i32_f32_e32 v96, v107
	v_pk_fma_f32 v[110:111], v[108:109], s[92:93], v[190:191] op_sel_hi:[1,0,0]
	v_ldexp_f32 v83, 1.0, v83
	v_pk_fma_f32 v[110:111], v[108:109], v[110:111], s[94:95] op_sel_hi:[1,1,0]
	v_ldexp_f32 v96, 1.0, v96
	v_pk_fma_f32 v[110:111], v[108:109], v[110:111], s[96:97] op_sel_hi:[1,1,0]
	v_cmp_eq_f32_e32 vcc, s95, v107
	v_pk_fma_f32 v[110:111], v[108:109], v[110:111], s[36:37] op_sel_hi:[1,1,0]
	v_cmp_eq_f32_e64 s[6:7], s95, v106
	v_pk_fma_f32 v[110:111], v[108:109], v[110:111], 0.5 op_sel_hi:[1,1,0]
	v_cndmask_b32_e32 v107, v96, v240, vcc
	v_pk_mul_f32 v[110:111], v[108:109], v[110:111]
	v_cndmask_b32_e64 v106, v83, v240, s[6:7]
	v_pk_fma_f32 v[108:109], v[108:109], v[110:111], v[108:109]
	v_pk_add_f32 v[110:111], v[106:107], -1.0 op_sel_hi:[1,0]
	v_exp_f32_e32 v105, v105
	v_pk_fma_f32 v[106:107], v[106:107], v[108:109], v[110:111]
	s_nop 0
	v_pk_add_f32 v[108:109], v[106:107], v[106:107]
	s_nop 0
	v_cndmask_b32_e32 v83, v107, v109, vcc
	v_cndmask_b32_e64 v96, v106, v108, s[6:7]
	v_cmp_nlt_f32_e32 vcc, s37, v100
	s_nop 1
	v_cndmask_b32_e64 v96, v239, -v96, vcc
	v_cmp_nlt_f32_e32 vcc, s37, v101
	s_nop 1
	v_cndmask_b32_e64 v83, v239, -v83, vcc
	v_cmp_ngt_f32_e32 vcc, s60, v101
	s_nop 1
	v_cndmask_b32_e32 v107, 1.0, v83, vcc
	v_cmp_ngt_f32_e32 vcc, s60, v100
	s_nop 1
	v_cndmask_b32_e32 v106, 1.0, v96, vcc

.LBB0_1120:
	s_or_b64 exec, exec, s[6:7]
	s_waitcnt lgkmcnt(4)
	v_pk_add_f32 v[98:99], v[86:87], v[210:211]
	v_sqrt_f32_e32 v106, v106
	v_pk_mul_f32 v[98:99], v[98:99], s[56:57] op_sel_hi:[1,0]
	v_sqrt_f32_e32 v107, v107
	v_exp_f32_e32 v98, v98
	v_exp_f32_e32 v99, v99
	v_mul_f32_e32 v2, v104, v2
	v_lshl_add_u64 v[100:101], v[88:89], 0, s[18:19]
	v_pk_add_f32 v[98:99], v[98:99], 1.0 op_sel_hi:[1,0]
	s_nop 0
	v_rcp_f32_e32 v108, v98
	v_rcp_f32_e32 v109, v99
	v_lshl_add_u64 v[98:99], v[90:91], 0, s[18:19]
	v_mov_b32_dpp v96, v2 quad_perm:[1,0,3,2] row_mask:0xf bank_mask:0xf bound_ctrl:1
	v_pk_mul_f32 v[106:107], v[108:109], v[106:107]
	s_waitcnt lgkmcnt(3)
	v_pk_mul_f32 v[102:103], v[212:213], v[106:107]
	s_nop 0
	v_fma_f32 v83, v104, v97, v102
	s_nop 1
	v_mov_b32_dpp v97, v83 quad_perm:[1,0,3,2] row_mask:0xf bank_mask:0xf bound_ctrl:1
	s_and_saveexec_b64 s[6:7], s[4:5]
	s_cbranch_execz .LBB0_1122
	v_cvt_pk_bf16_f32 v97, v83, v97
	global_store_dword v[100:101], v97, off
	v_cvt_pk_bf16_f32 v96, v2, v96
	global_store_dword v[98:99], v96, off

.LBB0_1124:
	s_or_b64 exec, exec, s[6:7]
	ds_read2st64_b32 v[208:209], v81 offset0:4 offset1:5
	ds_read2st64_b32 v[210:211], v81 offset0:20 offset1:21
	ds_read2st64_b32 v[212:213], v81 offset0:36 offset1:37
	s_waitcnt lgkmcnt(5)
	v_pk_add_f32 v[106:107], v[84:85], v[214:215]
	s_nop 0
	v_pk_mul_f32 v[106:107], v[106:107], s[56:57] op_sel_hi:[1,0]
	s_nop 0
	v_exp_f32_e32 v106, v106
	v_exp_f32_e32 v107, v107
	s_nop 0
	v_pk_add_f32 v[106:107], v[106:107], 1.0 op_sel_hi:[1,0]
	s_nop 0
	v_rcp_f32_e32 v106, v106
	v_rcp_f32_e32 v107, v107
	s_nop 0
	v_pk_mul_f32 v[112:113], v[92:93], v[106:107]
	s_nop 0
	v_cmp_nlt_f32_e32 vcc, s97, v112
	v_cmp_nlt_f32_e64 s[6:7], s97, v113
	s_or_b64 s[6:7], vcc, s[6:7]
	v_pk_add_f32 v[108:109], v[112:113], v[112:113]
	s_and_saveexec_b64 s[26:27], s[6:7]
	s_xor_b64 s[26:27], exec, s[26:27]
	s_cbranch_execz .LBB0_1126
	v_mul_f32_e32 v83, 0x3fb8aa3b, v112
	v_exp_f32_e32 v106, v83
	v_mul_f32_e32 v83, 0x3fb8aa3b, v108
	v_mul_f32_e32 v102, 0x3fb8aa3b, v109
	v_rndne_f32_e32 v110, v83
	v_rndne_f32_e32 v111, v102
	v_mul_f32_e32 v107, 0x3fb8aa3b, v113
	v_pk_fma_f32 v[112:113], v[110:111], s[88:89], v[108:109] op_sel_hi:[1,0,1]
	v_cvt_i32_f32_e32 v83, v110
	v_pk_fma_f32 v[112:113], v[110:111], s[90:91], v[112:113] op_sel_hi:[1,0,1]
	v_cvt_i32_f32_e32 v102, v111
	v_pk_fma_f32 v[132:133], v[112:113], s[92:93], v[190:191] op_sel_hi:[1,0,0]
	v_ldexp_f32 v83, 1.0, v83
	v_pk_fma_f32 v[132:133], v[112:113], v[132:133], s[94:95] op_sel_hi:[1,1,0]
	v_ldexp_f32 v102, 1.0, v102
	v_pk_fma_f32 v[132:133], v[112:113], v[132:133], s[96:97] op_sel_hi:[1,1,0]
	v_cmp_eq_f32_e32 vcc, s95, v111
	v_pk_fma_f32 v[132:133], v[112:113], v[132:133], s[36:37] op_sel_hi:[1,1,0]
	v_cmp_eq_f32_e64 s[6:7], s95, v110
	v_pk_fma_f32 v[132:133], v[112:113], v[132:133], 0.5 op_sel_hi:[1,1,0]
	v_cndmask_b32_e32 v111, v102, v240, vcc
	v_pk_mul_f32 v[132:133], v[112:113], v[132:133]
	v_cndmask_b32_e64 v110, v83, v240, s[6:7]
	v_pk_fma_f32 v[112:113], v[112:113], v[132:133], v[112:113]
	v_pk_add_f32 v[132:133], v[110:111], -1.0 op_sel_hi:[1,0]
	v_exp_f32_e32 v107, v107
	v_pk_fma_f32 v[110:111], v[110:111], v[112:113], v[132:133]
	s_nop 0
	v_pk_add_f32 v[112:113], v[110:111], v[110:111]
	s_nop 0
	v_cndmask_b32_e32 v83, v111, v113, vcc
	v_cndmask_b32_e64 v102, v110, v112, s[6:7]
	v_cmp_nlt_f32_e32 vcc, s37, v108
	s_nop 1
	v_cndmask_b32_e64 v102, v239, -v102, vcc
	v_cmp_nlt_f32_e32 vcc, s37, v109
	s_nop 1
	v_cndmask_b32_e64 v83, v239, -v83, vcc
	v_cmp_ngt_f32_e32 vcc, s60, v109
	s_nop 1
	v_cndmask_b32_e32 v111, 1.0, v83, vcc
	v_cmp_ngt_f32_e32 vcc, s60, v108
	s_nop 1
	v_cndmask_b32_e32 v110, 1.0, v102, vcc

.LBB0_1128:
	s_or_b64 exec, exec, s[6:7]
	s_waitcnt lgkmcnt(4)
	v_pk_add_f32 v[104:105], v[86:87], v[216:217]
	v_sqrt_f32_e32 v108, v110
	v_pk_mul_f32 v[104:105], v[104:105], s[56:57] op_sel_hi:[1,0]
	v_sqrt_f32_e32 v109, v111
	v_exp_f32_e32 v104, v104
	v_exp_f32_e32 v105, v105
	v_mul_f32_e32 v2, v106, v2
	v_pk_add_f32 v[104:105], v[104:105], 1.0 op_sel_hi:[1,0]
	s_nop 0
	v_rcp_f32_e32 v104, v104
	v_rcp_f32_e32 v105, v105
	s_nop 0
	v_pk_mul_f32 v[104:105], v[104:105], v[108:109]
	s_waitcnt lgkmcnt(3)
	v_pk_mul_f32 v[96:97], v[218:219], v[104:105]
	s_nop 0
	v_fma_f32 v83, v106, v103, v96
	v_mov_b32_dpp v96, v2 quad_perm:[1,0,3,2] row_mask:0xf bank_mask:0xf bound_ctrl:1
	s_nop 0
	v_mov_b32_dpp v102, v83 quad_perm:[1,0,3,2] row_mask:0xf bank_mask:0xf bound_ctrl:1
	s_and_saveexec_b64 s[6:7], s[4:5]
	s_cbranch_execz .LBB0_1130
	v_cvt_pk_bf16_f32 v102, v83, v102
	global_store_dword v[100:101], v102, off offset:2048
	v_cvt_pk_bf16_f32 v96, v2, v96
	global_store_dword v[98:99], v96, off offset:2048
